# phase-1 h0 streaming loop rewritten by hand (mod rows hoisted, counted vmcnt double buffer)
# speedup vs baseline: 1.1467x; 1.0066x over previous
; DI unsigned pack2(float a, float b) { f2_t v = {a, b}; bf2_t r = __builtin_convertvector(v, bf2_t); return __builtin_bit_cast(unsigned, r); }
; DI void phase1(const Params& p) {
;     ...
;   for (int i0 = bid * NTHR + tid; i0 < T_ * 256; i0 += stp * 8) {
;     f32x4 xv[8];
; #pragma unroll
;     for (int u = 0; u < 8; ++u) {
;       const int i = i0 + u * stp;
;       if (i < T_ * 256) xv[u] = __builtin_nontemporal_load((const f32x4*)(p.x + (size_t)i * 4));
;     }
; #pragma unroll
;     for (int u = 0; u < 8; ++u) {
;       const int i = i0 + u * stp;
;       if (i < T_ * 256) {
;         const int t = i >> 8, c4 = (i & 255) * 4, b = t >> 14;
;         const float4 sh = *(const float4*)(mod + b * 3072 + c4);
;         const float4 sc = *(const float4*)(mod + b * 3072 + 1024 + c4);
;         uint2 o;
;         o.x = pack2(xv[u].x * (1.f + sc.x) + sh.x, xv[u].y * (1.f + sc.y) + sh.y);
;         o.y = pack2(xv[u].z * (1.f + sc.z) + sh.z, xv[u].w * (1.f + sc.w) + sh.w);
;         *(uint2*)(hy + (size_t)t * LDH + c4) = o;
;       }
;     }
;   }
.LBB0_11:
	v_readlane_b32 s62, v251, 13
	v_readlane_b32 s63, v251, 14
	s_mov_b64 s[4:5], -1
	s_mov_b64 s[22:23], 0
	v_writelane_b32 v254, s20, 23
	s_cmp_lt_i32 s20, 1
	s_mov_b64 s[0:1], 0
	s_movk_i32 s20, 0x1000
	s_cbranch_scc1 .LBB0_44
	v_readlane_b32 s0, v254, 23
	s_cmp_eq_u32 s0, 1
	s_mov_b64 s[0:1], -1
	s_cbranch_scc0 .LBB0_117
	v_mov_b32_e32 v54, v182
	v_readlane_b32 s0, v253, 25
	v_readlane_b32 s24, v251, 13
	v_readlane_b32 s25, v251, 14
	v_add_u32_e32 v32, s0, v54
	v_cmp_gt_i32_e32 vcc, s59, v32
	s_and_saveexec_b64 s[26:27], vcc
	s_cbranch_execz .LBB0_47
	v_readlane_b32 s0, v253, 23
	v_readlane_b32 s64, v251, 19
	s_add_u32 s28, s24, 0x8c04100
	v_lshl_add_u32 v52, v54, 2, s0
	v_readlane_b32 s0, v253, 26
	v_ashrrev_i32_e32 v33, 31, v32
	v_readlane_b32 s65, v251, 20
	v_add_u32_e32 v0, s0, v54
	s_waitcnt lgkmcnt(0)
	v_ashrrev_i32_e32 v1, 31, v0
	v_readlane_b32 s66, v251, 21
	v_readlane_b32 s67, v251, 22
	s_addc_u32 s29, s25, 0
	v_lshlrev_b64 v[34:35], 4, v[0:1]
	v_lshlrev_b64 v[36:37], 4, v[32:33]
	s_mov_b64 s[30:31], 0
	s_movk_i32 s67, 0x1ff
	s_movk_i32 s66, 0x60
	s_mov_b64 s[34:35], s[64:65]
	s_mov_b64 s[64:65], 0x80
	v_mov_b32_e32 v33, v32
	v_readlane_b32 s68, v251, 23
	v_readlane_b32 s69, v251, 24
	v_readlane_b32 s70, v251, 25
	v_readlane_b32 s71, v251, 26
	v_readlane_b32 s72, v251, 27
	v_readlane_b32 s73, v251, 28
	v_readlane_b32 s74, v251, 29
	v_readlane_b32 s75, v251, 30
	v_readlane_b32 s76, v251, 31
	v_readlane_b32 s77, v251, 32
	v_readlane_b32 s78, v251, 33
	v_readlane_b32 s79, v251, 34
	s_cmp_eq_u32 s38, 0x100000
	s_cbranch_scc0 .LBB0_16
	v_and_b32_e32 v60, 0xff, v32
	v_lshlrev_b32_e32 v61, 4, v60
	v_lshlrev_b32_e32 v62, 4, v32
	v_lshrrev_b32_e32 v63, 8, v32
	s_movk_i32 s0, 0x880
	v_mul_u32_u24_e32 v63, s0, v63
	v_lshl_add_u32 v63, v60, 3, v63
	s_add_u32 s0, s24, 0x0
	s_addc_u32 s1, s25, 0
	global_load_dwordx4 v[40:43], v61, s[0:1]
	s_add_u32 s0, s24, 0x1000
	s_addc_u32 s1, s25, 0
	global_load_dwordx4 v[44:47], v61, s[0:1]
	s_add_u32 s0, s24, 0x3000
	s_addc_u32 s1, s25, 0
	global_load_dwordx4 v[48:51], v61, s[0:1]
	s_add_u32 s0, s24, 0x4000
	s_addc_u32 s1, s25, 0
	global_load_dwordx4 v[56:59], v61, s[0:1]
	global_load_dwordx4 v[64:67], v62, s[34:35] nt
	v_add_u32_e32 v62, 0x200000, v62
	global_load_dwordx4 v[68:71], v62, s[34:35] nt
	v_add_u32_e32 v62, 0x200000, v62
	global_load_dwordx4 v[72:75], v62, s[34:35] nt
	v_add_u32_e32 v62, 0x200000, v62
	global_load_dwordx4 v[76:79], v62, s[34:35] nt
	v_add_u32_e32 v62, 0x200000, v62
	global_load_dwordx4 v[80:83], v62, s[34:35] nt
	v_add_u32_e32 v62, 0x200000, v62
	global_load_dwordx4 v[84:87], v62, s[34:35] nt
	v_add_u32_e32 v62, 0x200000, v62
	global_load_dwordx4 v[88:91], v62, s[34:35] nt
	v_add_u32_e32 v62, 0x200000, v62
	global_load_dwordx4 v[92:95], v62, s[34:35] nt
	v_add_u32_e32 v62, 0x200000, v62
	s_waitcnt vmcnt(8)
	v_add_f32_e32 v44, 1.0, v44
	v_add_f32_e32 v45, 1.0, v45
	v_add_f32_e32 v46, 1.0, v46
	v_add_f32_e32 v47, 1.0, v47
	v_add_f32_e32 v56, 1.0, v56
	v_add_f32_e32 v57, 1.0, v57
	v_add_f32_e32 v58, 1.0, v58
	v_add_f32_e32 v59, 1.0, v59
	global_load_dwordx4 v[96:99], v62, s[34:35] nt
	v_add_u32_e32 v62, 0x200000, v62
	global_load_dwordx4 v[100:103], v62, s[34:35] nt
	v_add_u32_e32 v62, 0x200000, v62
	global_load_dwordx4 v[104:107], v62, s[34:35] nt
	v_add_u32_e32 v62, 0x200000, v62
	global_load_dwordx4 v[108:111], v62, s[34:35] nt
	v_add_u32_e32 v62, 0x200000, v62
	global_load_dwordx4 v[112:115], v62, s[34:35] nt
	v_add_u32_e32 v62, 0x200000, v62
	global_load_dwordx4 v[116:119], v62, s[34:35] nt
	v_add_u32_e32 v62, 0x200000, v62
	global_load_dwordx4 v[120:123], v62, s[34:35] nt
	v_add_u32_e32 v62, 0x200000, v62
	global_load_dwordx4 v[124:127], v62, s[34:35] nt
	v_add_u32_e32 v62, 0x200000, v62
	s_waitcnt vmcnt(8)
	v_fma_f32 v64, v64, v44, v40
	v_fma_f32 v65, v65, v45, v41
	v_fma_f32 v66, v66, v46, v42
	v_fma_f32 v67, v67, v47, v43
	v_cvt_pk_bf16_f32 v64, v64, v65
	v_cvt_pk_bf16_f32 v65, v66, v67
	global_store_dwordx2 v63, v[64:65], s[28:29]
	v_add_u32_e32 v63, 0x110000, v63
	v_fma_f32 v68, v68, v44, v40
	v_fma_f32 v69, v69, v45, v41
	v_fma_f32 v70, v70, v46, v42
	v_fma_f32 v71, v71, v47, v43
	v_cvt_pk_bf16_f32 v68, v68, v69
	v_cvt_pk_bf16_f32 v69, v70, v71
	global_store_dwordx2 v63, v[68:69], s[28:29]
	v_add_u32_e32 v63, 0x110000, v63
	v_fma_f32 v72, v72, v44, v40
	v_fma_f32 v73, v73, v45, v41
	v_fma_f32 v74, v74, v46, v42
	v_fma_f32 v75, v75, v47, v43
	v_cvt_pk_bf16_f32 v72, v72, v73
	v_cvt_pk_bf16_f32 v73, v74, v75
	global_store_dwordx2 v63, v[72:73], s[28:29]
	v_add_u32_e32 v63, 0x110000, v63
	v_fma_f32 v76, v76, v44, v40
	v_fma_f32 v77, v77, v45, v41
	v_fma_f32 v78, v78, v46, v42
	v_fma_f32 v79, v79, v47, v43
	v_cvt_pk_bf16_f32 v76, v76, v77
	v_cvt_pk_bf16_f32 v77, v78, v79
	global_store_dwordx2 v63, v[76:77], s[28:29]
	v_add_u32_e32 v63, 0x110000, v63
	v_fma_f32 v80, v80, v44, v40
	v_fma_f32 v81, v81, v45, v41
	v_fma_f32 v82, v82, v46, v42
	v_fma_f32 v83, v83, v47, v43
	v_cvt_pk_bf16_f32 v80, v80, v81
	v_cvt_pk_bf16_f32 v81, v82, v83
	global_store_dwordx2 v63, v[80:81], s[28:29]
	v_add_u32_e32 v63, 0x110000, v63
	v_fma_f32 v84, v84, v44, v40
	v_fma_f32 v85, v85, v45, v41
	v_fma_f32 v86, v86, v46, v42
	v_fma_f32 v87, v87, v47, v43
	v_cvt_pk_bf16_f32 v84, v84, v85
	v_cvt_pk_bf16_f32 v85, v86, v87
	global_store_dwordx2 v63, v[84:85], s[28:29]
	v_add_u32_e32 v63, 0x110000, v63
	v_fma_f32 v88, v88, v44, v40
	v_fma_f32 v89, v89, v45, v41
	v_fma_f32 v90, v90, v46, v42
	v_fma_f32 v91, v91, v47, v43
	v_cvt_pk_bf16_f32 v88, v88, v89
	v_cvt_pk_bf16_f32 v89, v90, v91
	global_store_dwordx2 v63, v[88:89], s[28:29]
	v_add_u32_e32 v63, 0x110000, v63
	v_fma_f32 v92, v92, v44, v40
	v_fma_f32 v93, v93, v45, v41
	v_fma_f32 v94, v94, v46, v42
	v_fma_f32 v95, v95, v47, v43
	v_cvt_pk_bf16_f32 v92, v92, v93
	v_cvt_pk_bf16_f32 v93, v94, v95
	global_store_dwordx2 v63, v[92:93], s[28:29]
	v_add_u32_e32 v63, 0x110000, v63
	global_load_dwordx4 v[64:67], v62, s[34:35] nt
	v_add_u32_e32 v62, 0x200000, v62
	global_load_dwordx4 v[68:71], v62, s[34:35] nt
	v_add_u32_e32 v62, 0x200000, v62
	global_load_dwordx4 v[72:75], v62, s[34:35] nt
	v_add_u32_e32 v62, 0x200000, v62
	global_load_dwordx4 v[76:79], v62, s[34:35] nt
	v_add_u32_e32 v62, 0x200000, v62
	global_load_dwordx4 v[80:83], v62, s[34:35] nt
	v_add_u32_e32 v62, 0x200000, v62
	global_load_dwordx4 v[84:87], v62, s[34:35] nt
	v_add_u32_e32 v62, 0x200000, v62
	global_load_dwordx4 v[88:91], v62, s[34:35] nt
	v_add_u32_e32 v62, 0x200000, v62
	global_load_dwordx4 v[92:95], v62, s[34:35] nt
	v_add_u32_e32 v62, 0x200000, v62
	s_waitcnt vmcnt(16)
; DI unsigned pack2(float a, float b) { f2_t v = {a, b}; bf2_t r = __builtin_convertvector(v, bf2_t); return __builtin_bit_cast(unsigned, r); }
; DI void phase1(const Params& p) {
;     ...
; #pragma unroll
;     for (int u = 0; u < 8; ++u) {
;       const int i = i0 + u * stp;
;       if (i < T_ * 256) {
;         const int t = i >> 8, c4 = (i & 255) * 4, b = t >> 14;
;         const float4 sh = *(const float4*)(mod + b * 3072 + c4);
;         const float4 sc = *(const float4*)(mod + b * 3072 + 1024 + c4);
;         uint2 o;
;         o.x = pack2(xv[u].x * (1.f + sc.x) + sh.x, xv[u].y * (1.f + sc.y) + sh.y);
;         o.y = pack2(xv[u].z * (1.f + sc.z) + sh.z, xv[u].w * (1.f + sc.w) + sh.w);
;         *(uint2*)(hy + (size_t)t * LDH + c4) = o;
;       }
;     }
	v_fma_f32 v96, v96, v44, v40
	v_fma_f32 v97, v97, v45, v41
	v_fma_f32 v98, v98, v46, v42
	v_fma_f32 v99, v99, v47, v43
	v_cvt_pk_bf16_f32 v96, v96, v97
	v_cvt_pk_bf16_f32 v97, v98, v99
	global_store_dwordx2 v63, v[96:97], s[28:29]
	v_add_u32_e32 v63, 0x110000, v63
	v_fma_f32 v100, v100, v44, v40
	v_fma_f32 v101, v101, v45, v41
	v_fma_f32 v102, v102, v46, v42
	v_fma_f32 v103, v103, v47, v43
	v_cvt_pk_bf16_f32 v100, v100, v101
	v_cvt_pk_bf16_f32 v101, v102, v103
	global_store_dwordx2 v63, v[100:101], s[28:29]
	v_add_u32_e32 v63, 0x110000, v63
	v_fma_f32 v104, v104, v44, v40
	v_fma_f32 v105, v105, v45, v41
	v_fma_f32 v106, v106, v46, v42
	v_fma_f32 v107, v107, v47, v43
	v_cvt_pk_bf16_f32 v104, v104, v105
	v_cvt_pk_bf16_f32 v105, v106, v107
	global_store_dwordx2 v63, v[104:105], s[28:29]
	v_add_u32_e32 v63, 0x110000, v63
	v_fma_f32 v108, v108, v44, v40
	v_fma_f32 v109, v109, v45, v41
	v_fma_f32 v110, v110, v46, v42
	v_fma_f32 v111, v111, v47, v43
	v_cvt_pk_bf16_f32 v108, v108, v109
	v_cvt_pk_bf16_f32 v109, v110, v111
	global_store_dwordx2 v63, v[108:109], s[28:29]
	v_add_u32_e32 v63, 0x110000, v63
	v_fma_f32 v112, v112, v44, v40
	v_fma_f32 v113, v113, v45, v41
	v_fma_f32 v114, v114, v46, v42
	v_fma_f32 v115, v115, v47, v43
	v_cvt_pk_bf16_f32 v112, v112, v113
	v_cvt_pk_bf16_f32 v113, v114, v115
	global_store_dwordx2 v63, v[112:113], s[28:29]
	v_add_u32_e32 v63, 0x110000, v63
	v_fma_f32 v116, v116, v44, v40
	v_fma_f32 v117, v117, v45, v41
	v_fma_f32 v118, v118, v46, v42
	v_fma_f32 v119, v119, v47, v43
	v_cvt_pk_bf16_f32 v116, v116, v117
	v_cvt_pk_bf16_f32 v117, v118, v119
	global_store_dwordx2 v63, v[116:117], s[28:29]
	v_add_u32_e32 v63, 0x110000, v63
	v_fma_f32 v120, v120, v44, v40
	v_fma_f32 v121, v121, v45, v41
	v_fma_f32 v122, v122, v46, v42
	v_fma_f32 v123, v123, v47, v43
	v_cvt_pk_bf16_f32 v120, v120, v121
	v_cvt_pk_bf16_f32 v121, v122, v123
	global_store_dwordx2 v63, v[120:121], s[28:29]
	v_add_u32_e32 v63, 0x110000, v63
	v_fma_f32 v124, v124, v44, v40
	v_fma_f32 v125, v125, v45, v41
	v_fma_f32 v126, v126, v46, v42
	v_fma_f32 v127, v127, v47, v43
	v_cvt_pk_bf16_f32 v124, v124, v125
	v_cvt_pk_bf16_f32 v125, v126, v127
	global_store_dwordx2 v63, v[124:125], s[28:29]
	v_add_u32_e32 v63, 0x110000, v63
	global_load_dwordx4 v[96:99], v62, s[34:35] nt
	v_add_u32_e32 v62, 0x200000, v62
	global_load_dwordx4 v[100:103], v62, s[34:35] nt
	v_add_u32_e32 v62, 0x200000, v62
	global_load_dwordx4 v[104:107], v62, s[34:35] nt
	v_add_u32_e32 v62, 0x200000, v62
	global_load_dwordx4 v[108:111], v62, s[34:35] nt
	v_add_u32_e32 v62, 0x200000, v62
	global_load_dwordx4 v[112:115], v62, s[34:35] nt
	v_add_u32_e32 v62, 0x200000, v62
	global_load_dwordx4 v[116:119], v62, s[34:35] nt
	v_add_u32_e32 v62, 0x200000, v62
	global_load_dwordx4 v[120:123], v62, s[34:35] nt
	v_add_u32_e32 v62, 0x200000, v62
	global_load_dwordx4 v[124:127], v62, s[34:35] nt
	v_add_u32_e32 v62, 0x200000, v62
	s_waitcnt vmcnt(16)
	v_fma_f32 v64, v64, v44, v40
	v_fma_f32 v65, v65, v45, v41
	v_fma_f32 v66, v66, v46, v42
	v_fma_f32 v67, v67, v47, v43
	v_cvt_pk_bf16_f32 v64, v64, v65
	v_cvt_pk_bf16_f32 v65, v66, v67
	global_store_dwordx2 v63, v[64:65], s[28:29]
	v_add_u32_e32 v63, 0x110000, v63
	v_fma_f32 v68, v68, v44, v40
	v_fma_f32 v69, v69, v45, v41
	v_fma_f32 v70, v70, v46, v42
	v_fma_f32 v71, v71, v47, v43
	v_cvt_pk_bf16_f32 v68, v68, v69
	v_cvt_pk_bf16_f32 v69, v70, v71
	global_store_dwordx2 v63, v[68:69], s[28:29]
	v_add_u32_e32 v63, 0x110000, v63
	v_fma_f32 v72, v72, v44, v40
	v_fma_f32 v73, v73, v45, v41
	v_fma_f32 v74, v74, v46, v42
	v_fma_f32 v75, v75, v47, v43
	v_cvt_pk_bf16_f32 v72, v72, v73
	v_cvt_pk_bf16_f32 v73, v74, v75
	global_store_dwordx2 v63, v[72:73], s[28:29]
	v_add_u32_e32 v63, 0x110000, v63
	v_fma_f32 v76, v76, v44, v40
	v_fma_f32 v77, v77, v45, v41
	v_fma_f32 v78, v78, v46, v42
	v_fma_f32 v79, v79, v47, v43
	v_cvt_pk_bf16_f32 v76, v76, v77
	v_cvt_pk_bf16_f32 v77, v78, v79
	global_store_dwordx2 v63, v[76:77], s[28:29]
	v_add_u32_e32 v63, 0x110000, v63
	v_fma_f32 v80, v80, v44, v40
	v_fma_f32 v81, v81, v45, v41
	v_fma_f32 v82, v82, v46, v42
	v_fma_f32 v83, v83, v47, v43
	v_cvt_pk_bf16_f32 v80, v80, v81
	v_cvt_pk_bf16_f32 v81, v82, v83
	global_store_dwordx2 v63, v[80:81], s[28:29]
	v_add_u32_e32 v63, 0x110000, v63
	v_fma_f32 v84, v84, v44, v40
	v_fma_f32 v85, v85, v45, v41
	v_fma_f32 v86, v86, v46, v42
	v_fma_f32 v87, v87, v47, v43
	v_cvt_pk_bf16_f32 v84, v84, v85
	v_cvt_pk_bf16_f32 v85, v86, v87
	global_store_dwordx2 v63, v[84:85], s[28:29]
	v_add_u32_e32 v63, 0x110000, v63
	v_fma_f32 v88, v88, v44, v40
	v_fma_f32 v89, v89, v45, v41
	v_fma_f32 v90, v90, v46, v42
	v_fma_f32 v91, v91, v47, v43
	v_cvt_pk_bf16_f32 v88, v88, v89
	v_cvt_pk_bf16_f32 v89, v90, v91
	global_store_dwordx2 v63, v[88:89], s[28:29]
	v_add_u32_e32 v63, 0x110000, v63
	v_fma_f32 v92, v92, v44, v40
	v_fma_f32 v93, v93, v45, v41
	v_fma_f32 v94, v94, v46, v42
	v_fma_f32 v95, v95, v47, v43
	v_cvt_pk_bf16_f32 v92, v92, v93
	v_cvt_pk_bf16_f32 v93, v94, v95
	global_store_dwordx2 v63, v[92:93], s[28:29]
	v_add_u32_e32 v63, 0x110000, v63
	global_load_dwordx4 v[64:67], v62, s[34:35] nt
	v_add_u32_e32 v62, 0x200000, v62
	global_load_dwordx4 v[68:71], v62, s[34:35] nt
	v_add_u32_e32 v62, 0x200000, v62
	global_load_dwordx4 v[72:75], v62, s[34:35] nt
	v_add_u32_e32 v62, 0x200000, v62
	global_load_dwordx4 v[76:79], v62, s[34:35] nt
	v_add_u32_e32 v62, 0x200000, v62
	global_load_dwordx4 v[80:83], v62, s[34:35] nt
	v_add_u32_e32 v62, 0x200000, v62
	global_load_dwordx4 v[84:87], v62, s[34:35] nt
	v_add_u32_e32 v62, 0x200000, v62
	global_load_dwordx4 v[88:91], v62, s[34:35] nt
	v_add_u32_e32 v62, 0x200000, v62
	global_load_dwordx4 v[92:95], v62, s[34:35] nt
	v_add_u32_e32 v62, 0x200000, v62
	s_waitcnt vmcnt(16)
; DI unsigned pack2(float a, float b) { f2_t v = {a, b}; bf2_t r = __builtin_convertvector(v, bf2_t); return __builtin_bit_cast(unsigned, r); }
; DI void phase1(const Params& p) {
;     ...
; #pragma unroll
;     for (int u = 0; u < 8; ++u) {
;       const int i = i0 + u * stp;
;       if (i < T_ * 256) {
;         const int t = i >> 8, c4 = (i & 255) * 4, b = t >> 14;
;         const float4 sh = *(const float4*)(mod + b * 3072 + c4);
;         const float4 sc = *(const float4*)(mod + b * 3072 + 1024 + c4);
;         uint2 o;
;         o.x = pack2(xv[u].x * (1.f + sc.x) + sh.x, xv[u].y * (1.f + sc.y) + sh.y);
;         o.y = pack2(xv[u].z * (1.f + sc.z) + sh.z, xv[u].w * (1.f + sc.w) + sh.w);
;         *(uint2*)(hy + (size_t)t * LDH + c4) = o;
;       }
;     }
	v_fma_f32 v96, v96, v44, v40
	v_fma_f32 v97, v97, v45, v41
	v_fma_f32 v98, v98, v46, v42
	v_fma_f32 v99, v99, v47, v43
	v_cvt_pk_bf16_f32 v96, v96, v97
	v_cvt_pk_bf16_f32 v97, v98, v99
	global_store_dwordx2 v63, v[96:97], s[28:29]
	v_add_u32_e32 v63, 0x110000, v63
	v_fma_f32 v100, v100, v44, v40
	v_fma_f32 v101, v101, v45, v41
	v_fma_f32 v102, v102, v46, v42
	v_fma_f32 v103, v103, v47, v43
	v_cvt_pk_bf16_f32 v100, v100, v101
	v_cvt_pk_bf16_f32 v101, v102, v103
	global_store_dwordx2 v63, v[100:101], s[28:29]
	v_add_u32_e32 v63, 0x110000, v63
	v_fma_f32 v104, v104, v44, v40
	v_fma_f32 v105, v105, v45, v41
	v_fma_f32 v106, v106, v46, v42
	v_fma_f32 v107, v107, v47, v43
	v_cvt_pk_bf16_f32 v104, v104, v105
	v_cvt_pk_bf16_f32 v105, v106, v107
	global_store_dwordx2 v63, v[104:105], s[28:29]
	v_add_u32_e32 v63, 0x110000, v63
	v_fma_f32 v108, v108, v44, v40
	v_fma_f32 v109, v109, v45, v41
	v_fma_f32 v110, v110, v46, v42
	v_fma_f32 v111, v111, v47, v43
	v_cvt_pk_bf16_f32 v108, v108, v109
	v_cvt_pk_bf16_f32 v109, v110, v111
	global_store_dwordx2 v63, v[108:109], s[28:29]
	v_add_u32_e32 v63, 0x110000, v63
	v_fma_f32 v112, v112, v44, v40
	v_fma_f32 v113, v113, v45, v41
	v_fma_f32 v114, v114, v46, v42
	v_fma_f32 v115, v115, v47, v43
	v_cvt_pk_bf16_f32 v112, v112, v113
	v_cvt_pk_bf16_f32 v113, v114, v115
	global_store_dwordx2 v63, v[112:113], s[28:29]
	v_add_u32_e32 v63, 0x110000, v63
	v_fma_f32 v116, v116, v44, v40
	v_fma_f32 v117, v117, v45, v41
	v_fma_f32 v118, v118, v46, v42
	v_fma_f32 v119, v119, v47, v43
	v_cvt_pk_bf16_f32 v116, v116, v117
	v_cvt_pk_bf16_f32 v117, v118, v119
	global_store_dwordx2 v63, v[116:117], s[28:29]
	v_add_u32_e32 v63, 0x110000, v63
	v_fma_f32 v120, v120, v44, v40
	v_fma_f32 v121, v121, v45, v41
	v_fma_f32 v122, v122, v46, v42
	v_fma_f32 v123, v123, v47, v43
	v_cvt_pk_bf16_f32 v120, v120, v121
	v_cvt_pk_bf16_f32 v121, v122, v123
	global_store_dwordx2 v63, v[120:121], s[28:29]
	v_add_u32_e32 v63, 0x110000, v63
	v_fma_f32 v124, v124, v44, v40
	v_fma_f32 v125, v125, v45, v41
	v_fma_f32 v126, v126, v46, v42
	v_fma_f32 v127, v127, v47, v43
	v_cvt_pk_bf16_f32 v124, v124, v125
	v_cvt_pk_bf16_f32 v125, v126, v127
	global_store_dwordx2 v63, v[124:125], s[28:29]
	v_add_u32_e32 v63, 0x110000, v63
	global_load_dwordx4 v[96:99], v62, s[34:35] nt
	v_add_u32_e32 v62, 0x200000, v62
	global_load_dwordx4 v[100:103], v62, s[34:35] nt
	v_add_u32_e32 v62, 0x200000, v62
	global_load_dwordx4 v[104:107], v62, s[34:35] nt
	v_add_u32_e32 v62, 0x200000, v62
	global_load_dwordx4 v[108:111], v62, s[34:35] nt
	v_add_u32_e32 v62, 0x200000, v62
	global_load_dwordx4 v[112:115], v62, s[34:35] nt
	v_add_u32_e32 v62, 0x200000, v62
	global_load_dwordx4 v[116:119], v62, s[34:35] nt
	v_add_u32_e32 v62, 0x200000, v62
	global_load_dwordx4 v[120:123], v62, s[34:35] nt
	v_add_u32_e32 v62, 0x200000, v62
	global_load_dwordx4 v[124:127], v62, s[34:35] nt
	v_add_u32_e32 v62, 0x200000, v62
	s_waitcnt vmcnt(16)
	v_fma_f32 v64, v64, v56, v48
	v_fma_f32 v65, v65, v57, v49
	v_fma_f32 v66, v66, v58, v50
	v_fma_f32 v67, v67, v59, v51
	v_cvt_pk_bf16_f32 v64, v64, v65
	v_cvt_pk_bf16_f32 v65, v66, v67
	global_store_dwordx2 v63, v[64:65], s[28:29]
	v_add_u32_e32 v63, 0x110000, v63
	v_fma_f32 v68, v68, v56, v48
	v_fma_f32 v69, v69, v57, v49
	v_fma_f32 v70, v70, v58, v50
	v_fma_f32 v71, v71, v59, v51
	v_cvt_pk_bf16_f32 v68, v68, v69
	v_cvt_pk_bf16_f32 v69, v70, v71
	global_store_dwordx2 v63, v[68:69], s[28:29]
	v_add_u32_e32 v63, 0x110000, v63
	v_fma_f32 v72, v72, v56, v48
	v_fma_f32 v73, v73, v57, v49
	v_fma_f32 v74, v74, v58, v50
	v_fma_f32 v75, v75, v59, v51
	v_cvt_pk_bf16_f32 v72, v72, v73
	v_cvt_pk_bf16_f32 v73, v74, v75
	global_store_dwordx2 v63, v[72:73], s[28:29]
	v_add_u32_e32 v63, 0x110000, v63
	v_fma_f32 v76, v76, v56, v48
	v_fma_f32 v77, v77, v57, v49
	v_fma_f32 v78, v78, v58, v50
	v_fma_f32 v79, v79, v59, v51
	v_cvt_pk_bf16_f32 v76, v76, v77
	v_cvt_pk_bf16_f32 v77, v78, v79
	global_store_dwordx2 v63, v[76:77], s[28:29]
	v_add_u32_e32 v63, 0x110000, v63
	v_fma_f32 v80, v80, v56, v48
	v_fma_f32 v81, v81, v57, v49
	v_fma_f32 v82, v82, v58, v50
	v_fma_f32 v83, v83, v59, v51
	v_cvt_pk_bf16_f32 v80, v80, v81
	v_cvt_pk_bf16_f32 v81, v82, v83
	global_store_dwordx2 v63, v[80:81], s[28:29]
	v_add_u32_e32 v63, 0x110000, v63
	v_fma_f32 v84, v84, v56, v48
	v_fma_f32 v85, v85, v57, v49
	v_fma_f32 v86, v86, v58, v50
	v_fma_f32 v87, v87, v59, v51
	v_cvt_pk_bf16_f32 v84, v84, v85
	v_cvt_pk_bf16_f32 v85, v86, v87
	global_store_dwordx2 v63, v[84:85], s[28:29]
	v_add_u32_e32 v63, 0x110000, v63
	v_fma_f32 v88, v88, v56, v48
	v_fma_f32 v89, v89, v57, v49
	v_fma_f32 v90, v90, v58, v50
	v_fma_f32 v91, v91, v59, v51
	v_cvt_pk_bf16_f32 v88, v88, v89
	v_cvt_pk_bf16_f32 v89, v90, v91
	global_store_dwordx2 v63, v[88:89], s[28:29]
	v_add_u32_e32 v63, 0x110000, v63
	v_fma_f32 v92, v92, v56, v48
	v_fma_f32 v93, v93, v57, v49
	v_fma_f32 v94, v94, v58, v50
	v_fma_f32 v95, v95, v59, v51
	v_cvt_pk_bf16_f32 v92, v92, v93
	v_cvt_pk_bf16_f32 v93, v94, v95
	global_store_dwordx2 v63, v[92:93], s[28:29]
	v_add_u32_e32 v63, 0x110000, v63
	global_load_dwordx4 v[64:67], v62, s[34:35] nt
	v_add_u32_e32 v62, 0x200000, v62
	global_load_dwordx4 v[68:71], v62, s[34:35] nt
	v_add_u32_e32 v62, 0x200000, v62
	global_load_dwordx4 v[72:75], v62, s[34:35] nt
	v_add_u32_e32 v62, 0x200000, v62
	global_load_dwordx4 v[76:79], v62, s[34:35] nt
	v_add_u32_e32 v62, 0x200000, v62
	global_load_dwordx4 v[80:83], v62, s[34:35] nt
	v_add_u32_e32 v62, 0x200000, v62
	global_load_dwordx4 v[84:87], v62, s[34:35] nt
	v_add_u32_e32 v62, 0x200000, v62
	global_load_dwordx4 v[88:91], v62, s[34:35] nt
	v_add_u32_e32 v62, 0x200000, v62
	global_load_dwordx4 v[92:95], v62, s[34:35] nt
	v_add_u32_e32 v62, 0x200000, v62
	s_waitcnt vmcnt(16)
; DI unsigned pack2(float a, float b) { f2_t v = {a, b}; bf2_t r = __builtin_convertvector(v, bf2_t); return __builtin_bit_cast(unsigned, r); }
; DI void phase1(const Params& p) {
;     ...
; #pragma unroll
;     for (int u = 0; u < 8; ++u) {
;       const int i = i0 + u * stp;
;       if (i < T_ * 256) {
;         const int t = i >> 8, c4 = (i & 255) * 4, b = t >> 14;
;         const float4 sh = *(const float4*)(mod + b * 3072 + c4);
;         const float4 sc = *(const float4*)(mod + b * 3072 + 1024 + c4);
;         uint2 o;
;         o.x = pack2(xv[u].x * (1.f + sc.x) + sh.x, xv[u].y * (1.f + sc.y) + sh.y);
;         o.y = pack2(xv[u].z * (1.f + sc.z) + sh.z, xv[u].w * (1.f + sc.w) + sh.w);
;         *(uint2*)(hy + (size_t)t * LDH + c4) = o;
;       }
;     }
	v_fma_f32 v96, v96, v56, v48
	v_fma_f32 v97, v97, v57, v49
	v_fma_f32 v98, v98, v58, v50
	v_fma_f32 v99, v99, v59, v51
	v_cvt_pk_bf16_f32 v96, v96, v97
	v_cvt_pk_bf16_f32 v97, v98, v99
	global_store_dwordx2 v63, v[96:97], s[28:29]
	v_add_u32_e32 v63, 0x110000, v63
	v_fma_f32 v100, v100, v56, v48
	v_fma_f32 v101, v101, v57, v49
	v_fma_f32 v102, v102, v58, v50
	v_fma_f32 v103, v103, v59, v51
	v_cvt_pk_bf16_f32 v100, v100, v101
	v_cvt_pk_bf16_f32 v101, v102, v103
	global_store_dwordx2 v63, v[100:101], s[28:29]
	v_add_u32_e32 v63, 0x110000, v63
	v_fma_f32 v104, v104, v56, v48
	v_fma_f32 v105, v105, v57, v49
	v_fma_f32 v106, v106, v58, v50
	v_fma_f32 v107, v107, v59, v51
	v_cvt_pk_bf16_f32 v104, v104, v105
	v_cvt_pk_bf16_f32 v105, v106, v107
	global_store_dwordx2 v63, v[104:105], s[28:29]
	v_add_u32_e32 v63, 0x110000, v63
	v_fma_f32 v108, v108, v56, v48
	v_fma_f32 v109, v109, v57, v49
	v_fma_f32 v110, v110, v58, v50
	v_fma_f32 v111, v111, v59, v51
	v_cvt_pk_bf16_f32 v108, v108, v109
	v_cvt_pk_bf16_f32 v109, v110, v111
	global_store_dwordx2 v63, v[108:109], s[28:29]
	v_add_u32_e32 v63, 0x110000, v63
	v_fma_f32 v112, v112, v56, v48
	v_fma_f32 v113, v113, v57, v49
	v_fma_f32 v114, v114, v58, v50
	v_fma_f32 v115, v115, v59, v51
	v_cvt_pk_bf16_f32 v112, v112, v113
	v_cvt_pk_bf16_f32 v113, v114, v115
	global_store_dwordx2 v63, v[112:113], s[28:29]
	v_add_u32_e32 v63, 0x110000, v63
	v_fma_f32 v116, v116, v56, v48
	v_fma_f32 v117, v117, v57, v49
	v_fma_f32 v118, v118, v58, v50
	v_fma_f32 v119, v119, v59, v51
	v_cvt_pk_bf16_f32 v116, v116, v117
	v_cvt_pk_bf16_f32 v117, v118, v119
	global_store_dwordx2 v63, v[116:117], s[28:29]
	v_add_u32_e32 v63, 0x110000, v63
	v_fma_f32 v120, v120, v56, v48
	v_fma_f32 v121, v121, v57, v49
	v_fma_f32 v122, v122, v58, v50
	v_fma_f32 v123, v123, v59, v51
	v_cvt_pk_bf16_f32 v120, v120, v121
	v_cvt_pk_bf16_f32 v121, v122, v123
	global_store_dwordx2 v63, v[120:121], s[28:29]
	v_add_u32_e32 v63, 0x110000, v63
	v_fma_f32 v124, v124, v56, v48
	v_fma_f32 v125, v125, v57, v49
	v_fma_f32 v126, v126, v58, v50
	v_fma_f32 v127, v127, v59, v51
	v_cvt_pk_bf16_f32 v124, v124, v125
	v_cvt_pk_bf16_f32 v125, v126, v127
	global_store_dwordx2 v63, v[124:125], s[28:29]
	v_add_u32_e32 v63, 0x110000, v63
	global_load_dwordx4 v[96:99], v62, s[34:35] nt
	v_add_u32_e32 v62, 0x200000, v62
	global_load_dwordx4 v[100:103], v62, s[34:35] nt
	v_add_u32_e32 v62, 0x200000, v62
	global_load_dwordx4 v[104:107], v62, s[34:35] nt
	v_add_u32_e32 v62, 0x200000, v62
	global_load_dwordx4 v[108:111], v62, s[34:35] nt
	v_add_u32_e32 v62, 0x200000, v62
	global_load_dwordx4 v[112:115], v62, s[34:35] nt
	v_add_u32_e32 v62, 0x200000, v62
	global_load_dwordx4 v[116:119], v62, s[34:35] nt
	v_add_u32_e32 v62, 0x200000, v62
	global_load_dwordx4 v[120:123], v62, s[34:35] nt
	v_add_u32_e32 v62, 0x200000, v62
	global_load_dwordx4 v[124:127], v62, s[34:35] nt
	v_add_u32_e32 v62, 0x200000, v62
	s_waitcnt vmcnt(16)
; DI unsigned pack2(float a, float b) { f2_t v = {a, b}; bf2_t r = __builtin_convertvector(v, bf2_t); return __builtin_bit_cast(unsigned, r); }
; DI void phase1(const Params& p) {
;     ...
; #pragma unroll
;     for (int u = 0; u < 8; ++u) {
;       const int i = i0 + u * stp;
;       if (i < T_ * 256) {
;         const int t = i >> 8, c4 = (i & 255) * 4, b = t >> 14;
;         const float4 sh = *(const float4*)(mod + b * 3072 + c4);
;         const float4 sc = *(const float4*)(mod + b * 3072 + 1024 + c4);
;         uint2 o;
;         o.x = pack2(xv[u].x * (1.f + sc.x) + sh.x, xv[u].y * (1.f + sc.y) + sh.y);
;         o.y = pack2(xv[u].z * (1.f + sc.z) + sh.z, xv[u].w * (1.f + sc.w) + sh.w);
;         *(uint2*)(hy + (size_t)t * LDH + c4) = o;
;       }
;     }
	v_fma_f32 v64, v64, v56, v48
	v_fma_f32 v65, v65, v57, v49
	v_fma_f32 v66, v66, v58, v50
	v_fma_f32 v67, v67, v59, v51
	v_cvt_pk_bf16_f32 v64, v64, v65
	v_cvt_pk_bf16_f32 v65, v66, v67
	global_store_dwordx2 v63, v[64:65], s[28:29]
	v_add_u32_e32 v63, 0x110000, v63
	v_fma_f32 v68, v68, v56, v48
	v_fma_f32 v69, v69, v57, v49
	v_fma_f32 v70, v70, v58, v50
	v_fma_f32 v71, v71, v59, v51
	v_cvt_pk_bf16_f32 v68, v68, v69
	v_cvt_pk_bf16_f32 v69, v70, v71
	global_store_dwordx2 v63, v[68:69], s[28:29]
	v_add_u32_e32 v63, 0x110000, v63
	v_fma_f32 v72, v72, v56, v48
	v_fma_f32 v73, v73, v57, v49
	v_fma_f32 v74, v74, v58, v50
	v_fma_f32 v75, v75, v59, v51
	v_cvt_pk_bf16_f32 v72, v72, v73
	v_cvt_pk_bf16_f32 v73, v74, v75
	global_store_dwordx2 v63, v[72:73], s[28:29]
	v_add_u32_e32 v63, 0x110000, v63
	v_fma_f32 v76, v76, v56, v48
	v_fma_f32 v77, v77, v57, v49
	v_fma_f32 v78, v78, v58, v50
	v_fma_f32 v79, v79, v59, v51
	v_cvt_pk_bf16_f32 v76, v76, v77
	v_cvt_pk_bf16_f32 v77, v78, v79
	global_store_dwordx2 v63, v[76:77], s[28:29]
	v_add_u32_e32 v63, 0x110000, v63
	v_fma_f32 v80, v80, v56, v48
	v_fma_f32 v81, v81, v57, v49
	v_fma_f32 v82, v82, v58, v50
	v_fma_f32 v83, v83, v59, v51
	v_cvt_pk_bf16_f32 v80, v80, v81
	v_cvt_pk_bf16_f32 v81, v82, v83
	global_store_dwordx2 v63, v[80:81], s[28:29]
	v_add_u32_e32 v63, 0x110000, v63
	v_fma_f32 v84, v84, v56, v48
	v_fma_f32 v85, v85, v57, v49
	v_fma_f32 v86, v86, v58, v50
	v_fma_f32 v87, v87, v59, v51
	v_cvt_pk_bf16_f32 v84, v84, v85
	v_cvt_pk_bf16_f32 v85, v86, v87
	global_store_dwordx2 v63, v[84:85], s[28:29]
	v_add_u32_e32 v63, 0x110000, v63
	v_fma_f32 v88, v88, v56, v48
	v_fma_f32 v89, v89, v57, v49
	v_fma_f32 v90, v90, v58, v50
	v_fma_f32 v91, v91, v59, v51
	v_cvt_pk_bf16_f32 v88, v88, v89
	v_cvt_pk_bf16_f32 v89, v90, v91
	global_store_dwordx2 v63, v[88:89], s[28:29]
	v_add_u32_e32 v63, 0x110000, v63
	v_fma_f32 v92, v92, v56, v48
	v_fma_f32 v93, v93, v57, v49
	v_fma_f32 v94, v94, v58, v50
	v_fma_f32 v95, v95, v59, v51
	v_cvt_pk_bf16_f32 v92, v92, v93
	v_cvt_pk_bf16_f32 v93, v94, v95
	global_store_dwordx2 v63, v[92:93], s[28:29]
	v_add_u32_e32 v63, 0x110000, v63
	s_waitcnt vmcnt(8)
	v_fma_f32 v96, v96, v56, v48
	v_fma_f32 v97, v97, v57, v49
	v_fma_f32 v98, v98, v58, v50
	v_fma_f32 v99, v99, v59, v51
	v_cvt_pk_bf16_f32 v96, v96, v97
	v_cvt_pk_bf16_f32 v97, v98, v99
	global_store_dwordx2 v63, v[96:97], s[28:29]
	v_add_u32_e32 v63, 0x110000, v63
	v_fma_f32 v100, v100, v56, v48
	v_fma_f32 v101, v101, v57, v49
	v_fma_f32 v102, v102, v58, v50
	v_fma_f32 v103, v103, v59, v51
	v_cvt_pk_bf16_f32 v100, v100, v101
	v_cvt_pk_bf16_f32 v101, v102, v103
	global_store_dwordx2 v63, v[100:101], s[28:29]
	v_add_u32_e32 v63, 0x110000, v63
	v_fma_f32 v104, v104, v56, v48
	v_fma_f32 v105, v105, v57, v49
	v_fma_f32 v106, v106, v58, v50
	v_fma_f32 v107, v107, v59, v51
	v_cvt_pk_bf16_f32 v104, v104, v105
	v_cvt_pk_bf16_f32 v105, v106, v107
	global_store_dwordx2 v63, v[104:105], s[28:29]
	v_add_u32_e32 v63, 0x110000, v63
	v_fma_f32 v108, v108, v56, v48
	v_fma_f32 v109, v109, v57, v49
	v_fma_f32 v110, v110, v58, v50
	v_fma_f32 v111, v111, v59, v51
	v_cvt_pk_bf16_f32 v108, v108, v109
	v_cvt_pk_bf16_f32 v109, v110, v111
	global_store_dwordx2 v63, v[108:109], s[28:29]
	v_add_u32_e32 v63, 0x110000, v63
	v_fma_f32 v112, v112, v56, v48
	v_fma_f32 v113, v113, v57, v49
	v_fma_f32 v114, v114, v58, v50
	v_fma_f32 v115, v115, v59, v51
	v_cvt_pk_bf16_f32 v112, v112, v113
	v_cvt_pk_bf16_f32 v113, v114, v115
	global_store_dwordx2 v63, v[112:113], s[28:29]
	v_add_u32_e32 v63, 0x110000, v63
	v_fma_f32 v116, v116, v56, v48
	v_fma_f32 v117, v117, v57, v49
	v_fma_f32 v118, v118, v58, v50
	v_fma_f32 v119, v119, v59, v51
	v_cvt_pk_bf16_f32 v116, v116, v117
	v_cvt_pk_bf16_f32 v117, v118, v119
	global_store_dwordx2 v63, v[116:117], s[28:29]
	v_add_u32_e32 v63, 0x110000, v63
	v_fma_f32 v120, v120, v56, v48
	v_fma_f32 v121, v121, v57, v49
	v_fma_f32 v122, v122, v58, v50
	v_fma_f32 v123, v123, v59, v51
	v_cvt_pk_bf16_f32 v120, v120, v121
	v_cvt_pk_bf16_f32 v121, v122, v123
	global_store_dwordx2 v63, v[120:121], s[28:29]
	v_add_u32_e32 v63, 0x110000, v63
	v_fma_f32 v124, v124, v56, v48
	v_fma_f32 v125, v125, v57, v49
	v_fma_f32 v126, v126, v58, v50
	v_fma_f32 v127, v127, v59, v51
	v_cvt_pk_bf16_f32 v124, v124, v125
	v_cvt_pk_bf16_f32 v125, v126, v127
	global_store_dwordx2 v63, v[124:125], s[28:29]
	v_add_u32_e32 v63, 0x110000, v63
	s_branch .LBB0_47
	s_branch .LBB0_16
